# P4 G23C kind-1 units: sum-of-squares records staged in LDS via LDS-DMA; epilogue rounds wait on lgkmcnt
# speedup vs baseline: 1.0019x; 1.0019x over previous
.LBB0_1554:
	s_ashr_i32 s31, s30, 31
	s_lshl_b64 s[38:39], s[30:31], 17
	s_cmp_eq_u32 s75, 1
	s_cselect_b32 s3, s52, 0xc80000
	s_cselect_b32 s31, 0xc80000, s52
	s_add_u32 s3, s80, s3
	s_addc_u32 s35, s81, 0
	s_add_u32 s38, s3, s38
	s_addc_u32 s39, s35, s39
	s_ashr_i32 s35, s34, 31
	s_lshl_b64 s[40:41], s[34:35], 17
	s_add_u32 s3, s80, s31
	s_addc_u32 s31, s81, 0
	s_add_u32 s40, s3, s40
	v_mov_b32_e32 v125, 0
	s_addc_u32 s41, s31, s41
	s_andn2_b64 vcc, exec, s[16:17]
	v_mov_b32_e32 v124, v125
	v_mov_b32_e32 v123, v125
	v_mov_b32_e32 v122, v125
	v_mov_b32_e32 v129, v125
	v_mov_b32_e32 v128, v125
	v_mov_b32_e32 v127, v125
	v_mov_b32_e32 v126, v125
	v_mov_b32_e32 v121, v125
	v_mov_b32_e32 v120, v125
	v_mov_b32_e32 v119, v125
	v_mov_b32_e32 v118, v125
	v_mov_b32_e32 v117, v125
	v_mov_b32_e32 v116, v125
	v_mov_b32_e32 v115, v125
	v_mov_b32_e32 v114, v125
	v_mov_b32_e32 v113, v125
	v_mov_b32_e32 v112, v125
	v_mov_b32_e32 v111, v125
	v_mov_b32_e32 v110, v125
	v_mov_b32_e32 v109, v125
	v_mov_b32_e32 v108, v125
	v_mov_b32_e32 v107, v125
	v_mov_b32_e32 v106, v125
	v_mov_b32_e32 v105, v125
	v_mov_b32_e32 v104, v125
	v_mov_b32_e32 v103, v125
	v_mov_b32_e32 v102, v125
	v_mov_b32_e32 v101, v125
	v_mov_b32_e32 v100, v125
	v_mov_b32_e32 v99, v125
	v_mov_b32_e32 v98, v125
	v_mov_b32_e32 v65, v125
	v_mov_b32_e32 v64, v125
	v_mov_b32_e32 v63, v125
	v_mov_b32_e32 v62, v125
	v_mov_b32_e32 v61, v125
	v_mov_b32_e32 v60, v125
	v_mov_b32_e32 v59, v125
	v_mov_b32_e32 v58, v125
	v_mov_b32_e32 v57, v125
	v_mov_b32_e32 v56, v125
	v_mov_b32_e32 v55, v125
	v_mov_b32_e32 v54, v125
	v_mov_b32_e32 v53, v125
	v_mov_b32_e32 v52, v125
	v_mov_b32_e32 v51, v125
	v_mov_b32_e32 v50, v125
	v_mov_b32_e32 v49, v125
	v_mov_b32_e32 v48, v125
	v_mov_b32_e32 v47, v125
	v_mov_b32_e32 v46, v125
	v_mov_b32_e32 v45, v125
	v_mov_b32_e32 v44, v125
	v_mov_b32_e32 v43, v125
	v_mov_b32_e32 v42, v125
	v_mov_b32_e32 v41, v125
	v_mov_b32_e32 v40, v125
	v_mov_b32_e32 v39, v125
	v_mov_b32_e32 v38, v125
	v_mov_b32_e32 v37, v125
	v_mov_b32_e32 v36, v125
	v_mov_b32_e32 v35, v125
	v_mov_b32_e32 v34, v125
	v_mov_b32_e32 v97, v125
	v_mov_b32_e32 v96, v125
	v_mov_b32_e32 v95, v125
	v_mov_b32_e32 v94, v125
	v_mov_b32_e32 v93, v125
	v_mov_b32_e32 v92, v125
	v_mov_b32_e32 v91, v125
	v_mov_b32_e32 v90, v125
	v_mov_b32_e32 v89, v125
	v_mov_b32_e32 v88, v125
	v_mov_b32_e32 v87, v125
	v_mov_b32_e32 v86, v125
	v_mov_b32_e32 v85, v125
	v_mov_b32_e32 v84, v125
	v_mov_b32_e32 v83, v125
	v_mov_b32_e32 v82, v125
	v_mov_b32_e32 v81, v125
	v_mov_b32_e32 v80, v125
	v_mov_b32_e32 v79, v125
	v_mov_b32_e32 v78, v125
	v_mov_b32_e32 v77, v125
	v_mov_b32_e32 v76, v125
	v_mov_b32_e32 v75, v125
	v_mov_b32_e32 v74, v125
	v_mov_b32_e32 v73, v125
	v_mov_b32_e32 v72, v125
	v_mov_b32_e32 v71, v125
	v_mov_b32_e32 v70, v125
	v_mov_b32_e32 v69, v125
	v_mov_b32_e32 v68, v125
	v_mov_b32_e32 v67, v125
	v_mov_b32_e32 v66, v125
	v_mov_b32_e32 v33, v125
	v_mov_b32_e32 v32, v125
	v_mov_b32_e32 v31, v125
	v_mov_b32_e32 v30, v125
	v_mov_b32_e32 v29, v125
	v_mov_b32_e32 v28, v125
	v_mov_b32_e32 v27, v125
	v_mov_b32_e32 v26, v125
	v_mov_b32_e32 v25, v125
	v_mov_b32_e32 v24, v125
	v_mov_b32_e32 v23, v125
	v_mov_b32_e32 v22, v125
	v_mov_b32_e32 v21, v125
	v_mov_b32_e32 v20, v125
	v_mov_b32_e32 v19, v125
	v_mov_b32_e32 v18, v125
	v_mov_b32_e32 v17, v125
	v_mov_b32_e32 v16, v125
	v_mov_b32_e32 v15, v125
	v_mov_b32_e32 v14, v125
	v_mov_b32_e32 v13, v125
	v_mov_b32_e32 v12, v125
	v_mov_b32_e32 v11, v125
	v_mov_b32_e32 v10, v125
	v_mov_b32_e32 v9, v125
	v_mov_b32_e32 v8, v125
	v_mov_b32_e32 v7, v125
	v_mov_b32_e32 v6, v125
	v_mov_b32_e32 v5, v125
	v_mov_b32_e32 v4, v125
	v_mov_b32_e32 v3, v125
	v_mov_b32_e32 v2, v125
	s_cbranch_vccnz .LBB0_1557
	s_and_b64 s[46:47], s[36:37], exec
	s_cselect_b32 s3, s39, s7
	s_cselect_b32 s31, s38, s6
	s_cselect_b32 s35, s41, s9
	s_cselect_b32 s45, s40, s8
	s_add_u32 s6, s6, 0x80
	s_addc_u32 s7, s7, 0
	s_add_u32 s46, s8, 0x100
	v_mov_b32_e32 v2, 0
	s_addc_u32 s47, s9, 0
	s_mov_b32 s8, 0
	v_mov_b32_e32 v3, v2
	v_mov_b32_e32 v4, v2
	v_mov_b32_e32 v5, v2
	v_mov_b32_e32 v6, v2
	v_mov_b32_e32 v7, v2
	v_mov_b32_e32 v8, v2
	v_mov_b32_e32 v9, v2
	v_mov_b32_e32 v10, v2
	v_mov_b32_e32 v11, v2
	v_mov_b32_e32 v12, v2
	v_mov_b32_e32 v13, v2
	v_mov_b32_e32 v14, v2
	v_mov_b32_e32 v15, v2
	v_mov_b32_e32 v16, v2
	v_mov_b32_e32 v17, v2
	v_mov_b32_e32 v18, v2
	v_mov_b32_e32 v19, v2
	v_mov_b32_e32 v20, v2
	v_mov_b32_e32 v21, v2
	v_mov_b32_e32 v22, v2
	v_mov_b32_e32 v23, v2
	v_mov_b32_e32 v24, v2
	v_mov_b32_e32 v25, v2
	v_mov_b32_e32 v26, v2
	v_mov_b32_e32 v27, v2
	v_mov_b32_e32 v28, v2
	v_mov_b32_e32 v29, v2
	v_mov_b32_e32 v30, v2
	v_mov_b32_e32 v31, v2
	v_mov_b32_e32 v32, v2
	v_mov_b32_e32 v33, v2
	v_mov_b32_e32 v66, v2
	v_mov_b32_e32 v67, v2
	v_mov_b32_e32 v68, v2
	v_mov_b32_e32 v69, v2
	v_mov_b32_e32 v70, v2
	v_mov_b32_e32 v71, v2
	v_mov_b32_e32 v72, v2
	v_mov_b32_e32 v73, v2
	v_mov_b32_e32 v74, v2
	v_mov_b32_e32 v75, v2
	v_mov_b32_e32 v76, v2
	v_mov_b32_e32 v77, v2
	v_mov_b32_e32 v78, v2
	v_mov_b32_e32 v79, v2
	v_mov_b32_e32 v80, v2
	v_mov_b32_e32 v81, v2
	v_mov_b32_e32 v82, v2
	v_mov_b32_e32 v83, v2
	v_mov_b32_e32 v84, v2
	v_mov_b32_e32 v85, v2
	v_mov_b32_e32 v86, v2
	v_mov_b32_e32 v87, v2
	v_mov_b32_e32 v88, v2
	v_mov_b32_e32 v89, v2
	v_mov_b32_e32 v90, v2
	v_mov_b32_e32 v91, v2
	v_mov_b32_e32 v92, v2
	v_mov_b32_e32 v93, v2
	v_mov_b32_e32 v94, v2
	v_mov_b32_e32 v95, v2
	v_mov_b32_e32 v96, v2
	v_mov_b32_e32 v97, v2
	v_mov_b32_e32 v34, v2
	v_mov_b32_e32 v35, v2
	v_mov_b32_e32 v36, v2
	v_mov_b32_e32 v37, v2
	v_mov_b32_e32 v38, v2
	v_mov_b32_e32 v39, v2
	v_mov_b32_e32 v40, v2
	v_mov_b32_e32 v41, v2
	v_mov_b32_e32 v42, v2
	v_mov_b32_e32 v43, v2
	v_mov_b32_e32 v44, v2
	v_mov_b32_e32 v45, v2
	v_mov_b32_e32 v46, v2
	v_mov_b32_e32 v47, v2
	v_mov_b32_e32 v48, v2
	v_mov_b32_e32 v49, v2
	v_mov_b32_e32 v50, v2
	v_mov_b32_e32 v51, v2
	v_mov_b32_e32 v52, v2
	v_mov_b32_e32 v53, v2
	v_mov_b32_e32 v54, v2
	v_mov_b32_e32 v55, v2
	v_mov_b32_e32 v56, v2
	v_mov_b32_e32 v57, v2
	v_mov_b32_e32 v58, v2
	v_mov_b32_e32 v59, v2
	v_mov_b32_e32 v60, v2
	v_mov_b32_e32 v61, v2
	v_mov_b32_e32 v62, v2
	v_mov_b32_e32 v63, v2
	v_mov_b32_e32 v64, v2
	v_mov_b32_e32 v65, v2
	v_mov_b32_e32 v98, v2
	v_mov_b32_e32 v99, v2
	v_mov_b32_e32 v100, v2
	v_mov_b32_e32 v101, v2
	v_mov_b32_e32 v102, v2
	v_mov_b32_e32 v103, v2
	v_mov_b32_e32 v104, v2
	v_mov_b32_e32 v105, v2
	v_mov_b32_e32 v106, v2
	v_mov_b32_e32 v107, v2
	v_mov_b32_e32 v108, v2
	v_mov_b32_e32 v109, v2
	v_mov_b32_e32 v110, v2
	v_mov_b32_e32 v111, v2
	v_mov_b32_e32 v112, v2
	v_mov_b32_e32 v113, v2
	v_mov_b32_e32 v114, v2
	v_mov_b32_e32 v115, v2
	v_mov_b32_e32 v116, v2
	v_mov_b32_e32 v117, v2
	v_mov_b32_e32 v118, v2
	v_mov_b32_e32 v119, v2
	v_mov_b32_e32 v120, v2
	v_mov_b32_e32 v121, v2
	v_mov_b32_e32 v126, v2
	v_mov_b32_e32 v127, v2
	v_mov_b32_e32 v128, v2
	v_mov_b32_e32 v129, v2
	v_mov_b32_e32 v122, v2
	v_mov_b32_e32 v123, v2
	v_mov_b32_e32 v124, v2
	v_mov_b32_e32 v125, v2
	s_cmp_eq_u32 s44, 2
	s_cbranch_scc1 .Lsst4_k2
	v_mbcnt_lo_u32_b32 v244, -1, 0
	v_mbcnt_hi_u32_b32 v244, -1, v244
	v_lshlrev_b32_e32 v244, 4, v244
	v_lshl_add_u32 v244, s62, 4, v244
	v_lshl_add_u32 v244, s42, 12, v244
	v_mov_b32_e32 v245, 0
	v_lshl_add_u64 v[244:245], v[244:245], 0, s[20:21]
	s_mov_b32 s99, 0x20400
	v_mov_b32_e32 v247, s99
	s_lshl_b32 s98, s62, 4
	s_add_i32 m0, s98, s99
	s_nop 0
	global_load_lds_dwordx4 v[244:245], off
	global_load_lds_dwordx4 v[244:245], off offset:2048
	s_branch .Lsst4_done
.Lsst4_k2:
	s_mov_b32 s98, s20
	s_mov_b32 s99, s21
	v_mbcnt_lo_u32_b32 v244, -1, 0
	v_mbcnt_hi_u32_b32 v244, -1, v244
	v_and_b32_e32 v245, 4, v244
	v_and_b32_e32 v244, 3, v244
	v_lshlrev_b32_e32 v245, 9, v245
	v_lshl_or_b32 v244, v244, 7, v245
	v_lshl_add_u32 v244, s63, 4, v244
	v_lshl_add_u32 v244, s28, 12, v244
	v_mov_b32_e32 v245, 0
	s_mov_b32 m0, 0x22800
	v_lshl_add_u64 v[244:245], v[244:245], 0, s[98:99]
	global_load_lds_dword v[244:245], off
.Lsst4_done:
.LBB0_1556:
	ds_read_b128 v[150:153], v172
	ds_read_b128 v[154:157], v172 offset:1024
	ds_read_b128 v[158:161], v172 offset:2048
	ds_read_b128 v[162:165], v172 offset:3072
	ds_read_b128 v[180:183], v173
	ds_read_b128 v[184:187], v173 offset:1024
	ds_read_b128 v[188:191], v173 offset:2048
	ds_read_b128 v[192:195], v173 offset:3072
	s_add_i32 s48, s8, 2
	s_add_u32 s49, s6, 0x80
	s_addc_u32 s9, s7, 0
	s_cmp_eq_u32 s64, s8
	s_cselect_b32 s8, s31, s49
	s_cselect_b32 s9, s3, s9
	s_cselect_b32 s85, s35, s47
	s_cselect_b32 s84, s45, s46
	s_cbranch_scc0 .Lpf_skip_3
	s_getpc_b64 s[98:99]
	s_mov_b32 m0, 0x22800
	v_lshlrev_b32_e32 v196, 7, v0
	global_load_lds_dword v196, s[98:99]

.LBB0_1566:
	s_lshl_b32 s3, s42, 8
	s_add_i32 s3, s3, s62
	v_or_b32_e32 v150, s3, v1
	v_cmp_lt_i32_e32 vcc, s70, v150
	s_and_saveexec_b64 s[6:7], vcc
	s_xor_b64 s[6:7], exec, s[6:7]
	s_add_i32 s8, s3, 0xffffc000
	s_lshr_b32 s8, s8, 8
	v_and_b32_e32 v138, 0xcf, v150
	v_or_b32_e32 v138, 0x1000, v138
	v_mov_b32_e32 v154, s8
	s_andn2_saveexec_b64 s[6:7], s[6:7]
	s_ashr_i32 s8, s3, 12
	v_and_b32_e32 v138, 0xfcf, v150
	v_mov_b32_e32 v154, s8
	s_or_b64 exec, exec, s[6:7]
	s_cmp_lg_u32 s44, 0
	s_cselect_b64 s[44:45], -1, 0
	v_ashrrev_i32_e32 v151, 31, v150
	v_lshlrev_b64 v[152:153], 4, v[150:151]
	s_and_b64 vcc, exec, s[44:45]
	s_cbranch_vccz .LBB0_1572
	v_and_b32_e32 v246, 0xff0, v152
	v_lshl_add_u64 v[156:157], s[20:21], 0, v[152:153]
	v_add_u32_e32 v246, v247, v246
	ds_read_b128 v[156:159], v246
	s_lshl_b32 s6, s28, 8
	s_or_b32 s6, s6, s63
	s_ashr_i32 s6, s6, 6
	v_lshl_add_u32 v151, v154, 3, s6
	v_mad_i64_i32 v[160:161], s[6:7], v151, s72, v[138:139]
	v_or_b32_e32 v151, 2, v151
	v_mad_i64_i32 v[162:163], s[6:7], v151, s72, v[138:139]
	v_mad_u64_u32 v[164:165], s[6:7], v160, s55, v[140:141]
	v_mad_i32_i24 v165, v161, s55, v165
	s_waitcnt lgkmcnt(0)
	v_mov_b32_e32 v180, v157
	v_mov_b32_e32 v181, v158
	v_mov_b32_e32 v157, v159
	v_pk_add_f32 v[156:157], v[180:181], v[156:157]
	v_mad_u64_u32 v[180:181], s[6:7], v162, s55, v[140:141]
	v_add_f32_e32 v151, v156, v157
	v_fmamk_f32 v151, v151, 0x3c000000, v175
	v_mul_f32_e32 v155, 0x4f800000, v151
	v_cmp_gt_f32_e32 vcc, s71, v151
	v_mad_i32_i24 v181, v163, s55, v181
	s_nop 0
	v_cndmask_b32_e32 v151, v151, v155, vcc
	v_sqrt_f32_e32 v155, v151
	s_nop 0
	v_add_u32_e32 v156, -1, v155
	v_add_u32_e32 v157, 1, v155
	v_fma_f32 v158, -v156, v155, v151
	v_fma_f32 v159, -v157, v155, v151
	v_cmp_ge_f32_e64 s[6:7], 0, v158
	s_nop 1
	v_cndmask_b32_e64 v155, v155, v156, s[6:7]
	v_cmp_lt_f32_e64 s[6:7], 0, v159
	s_nop 1
	v_cndmask_b32_e64 v155, v155, v157, s[6:7]
	v_mul_f32_e32 v156, 0x37800000, v155
	v_cndmask_b32_e32 v155, v155, v156, vcc
	v_cmp_class_f32_e32 vcc, v151, v176
	s_nop 1
	v_cndmask_b32_e32 v151, v155, v151, vcc
	v_div_scale_f32 v155, s[6:7], v151, v151, 1.0
	v_rcp_f32_e32 v156, v155
	v_div_scale_f32 v157, vcc, 1.0, v151, 1.0
	v_fma_f32 v158, -v155, v156, 1.0
	v_fmac_f32_e32 v156, v158, v156
	v_mul_f32_e32 v158, v157, v156
	v_fma_f32 v159, -v155, v158, v157
	v_fmac_f32_e32 v158, v159, v156
	v_fma_f32 v155, -v155, v158, v157
	v_div_fmas_f32 v155, v155, v156, v158
	v_div_fixup_f32 v156, v155, v151, 1.0
	v_pk_mul_f32 v[158:159], v[124:125], v[156:157] op_sel_hi:[1,0]
	v_pk_mul_f32 v[160:161], v[122:123], v[156:157] op_sel_hi:[1,0]
	v_pk_mul_f32 v[162:163], v[128:129], v[156:157] op_sel_hi:[1,0]
	v_pk_mul_f32 v[182:183], v[126:127], v[156:157] op_sel_hi:[1,0]
	v_pk_mul_f32 v[184:185], v[64:65], v[156:157] op_sel_hi:[1,0]
	v_pk_mul_f32 v[186:187], v[62:63], v[156:157] op_sel_hi:[1,0]
	v_pk_mul_f32 v[188:189], v[60:61], v[156:157] op_sel_hi:[1,0]
	v_pk_mul_f32 v[190:191], v[58:59], v[156:157] op_sel_hi:[1,0]
	v_cvt_pk_bf16_f32 v156, v160, v161
	v_cvt_pk_bf16_f32 v157, v158, v159
	v_cvt_pk_bf16_f32 v158, v182, v183
	v_cvt_pk_bf16_f32 v159, v162, v163
	v_cvt_pk_bf16_f32 v160, v186, v187
	v_cvt_pk_bf16_f32 v161, v184, v185
	v_cvt_pk_bf16_f32 v162, v190, v191
	v_cvt_pk_bf16_f32 v163, v188, v189
	global_store_dwordx4 v[164:165], v[156:159], off
	global_store_dwordx4 v[180:181], v[160:163], off
	s_cbranch_execz .LBB0_1573
	s_branch .LBB0_1581

.LBB0_1581:
	s_nop 1
	v_or_b32_e32 v152, 16, v150
	v_cmp_lt_i32_e32 vcc, s70, v152
	s_and_saveexec_b64 s[6:7], vcc
	s_xor_b64 s[6:7], exec, s[6:7]
	s_add_i32 s8, s3, 0xffffc000
	s_lshr_b32 s8, s8, 8
	v_and_b32_e32 v138, 0xdf, v152
	v_or_b32_e32 v138, 0x1000, v138
	v_mov_b32_e32 v151, s8
	s_andn2_saveexec_b64 s[6:7], s[6:7]
	s_ashr_i32 s8, s3, 12
	v_and_b32_e32 v138, 0xfdf, v152
	v_mov_b32_e32 v151, s8
	s_or_b64 exec, exec, s[6:7]
	v_ashrrev_i32_e32 v153, 31, v152
	v_cndmask_b32_e64 v154, 0, 1, s[44:45]
	v_cmp_ne_u32_e64 s[6:7], 1, v154
	s_andn2_b64 vcc, exec, s[44:45]
	v_lshlrev_b64 v[152:153], 4, v[152:153]
	s_cbranch_vccnz .LBB0_1587
	v_and_b32_e32 v246, 0xff0, v152
	v_lshl_add_u64 v[154:155], s[20:21], 0, v[152:153]
	v_add_u32_e32 v246, v247, v246
	ds_read_b128 v[154:157], v246
	s_lshl_b32 s8, s28, 8
	s_or_b32 s8, s8, s63
	s_ashr_i32 s8, s8, 6
	v_lshl_add_u32 v160, v151, 3, s8
	v_mad_i64_i32 v[158:159], s[8:9], v160, s72, v[138:139]
	v_or_b32_e32 v160, 2, v160
	v_mad_i64_i32 v[160:161], s[8:9], v160, s72, v[138:139]
	v_mad_u64_u32 v[162:163], s[8:9], v158, s55, v[140:141]
	v_mad_i32_i24 v163, v159, s55, v163
	s_waitcnt lgkmcnt(0)
	v_mov_b32_e32 v164, v155
	v_mov_b32_e32 v165, v156
	v_mov_b32_e32 v155, v157
	v_pk_add_f32 v[154:155], v[164:165], v[154:155]
	v_mad_u64_u32 v[164:165], s[8:9], v160, s55, v[140:141]
	v_add_f32_e32 v154, v154, v155
	v_fmamk_f32 v154, v154, 0x3c000000, v175
	v_mul_f32_e32 v155, 0x4f800000, v154
	v_cmp_gt_f32_e32 vcc, s71, v154
	v_mad_i32_i24 v165, v161, s55, v165
	s_nop 0
	v_cndmask_b32_e32 v154, v154, v155, vcc
	v_sqrt_f32_e32 v155, v154
	s_nop 0
	v_add_u32_e32 v156, -1, v155
	v_add_u32_e32 v157, 1, v155
	v_fma_f32 v158, -v156, v155, v154
	v_fma_f32 v159, -v157, v155, v154
	v_cmp_ge_f32_e64 s[8:9], 0, v158
	s_nop 1
	v_cndmask_b32_e64 v155, v155, v156, s[8:9]
	v_cmp_lt_f32_e64 s[8:9], 0, v159
	s_nop 1
	v_cndmask_b32_e64 v155, v155, v157, s[8:9]
	v_mul_f32_e32 v156, 0x37800000, v155
	v_cndmask_b32_e32 v155, v155, v156, vcc
	v_cmp_class_f32_e32 vcc, v154, v176
	s_nop 1
	v_cndmask_b32_e32 v154, v155, v154, vcc
	v_div_scale_f32 v155, s[8:9], v154, v154, 1.0
	v_rcp_f32_e32 v156, v155
	v_div_scale_f32 v157, vcc, 1.0, v154, 1.0
	v_fma_f32 v158, -v155, v156, 1.0
	v_fmac_f32_e32 v156, v158, v156
	v_mul_f32_e32 v158, v157, v156
	v_fma_f32 v159, -v155, v158, v157
	v_fmac_f32_e32 v158, v159, v156
	v_fma_f32 v155, -v155, v158, v157
	v_div_fmas_f32 v155, v155, v156, v158
	v_div_fixup_f32 v154, v155, v154, 1.0
	v_pk_mul_f32 v[156:157], v[120:121], v[154:155] op_sel_hi:[1,0]
	v_pk_mul_f32 v[158:159], v[118:119], v[154:155] op_sel_hi:[1,0]
	v_pk_mul_f32 v[160:161], v[116:117], v[154:155] op_sel_hi:[1,0]
	v_pk_mul_f32 v[180:181], v[114:115], v[154:155] op_sel_hi:[1,0]
	v_pk_mul_f32 v[182:183], v[56:57], v[154:155] op_sel_hi:[1,0]
	v_pk_mul_f32 v[184:185], v[54:55], v[154:155] op_sel_hi:[1,0]
	v_pk_mul_f32 v[186:187], v[52:53], v[154:155] op_sel_hi:[1,0]
	v_pk_mul_f32 v[188:189], v[50:51], v[154:155] op_sel_hi:[1,0]
	v_cvt_pk_bf16_f32 v154, v158, v159
	v_cvt_pk_bf16_f32 v155, v156, v157
	v_cvt_pk_bf16_f32 v156, v180, v181
	v_cvt_pk_bf16_f32 v157, v160, v161
	v_cvt_pk_bf16_f32 v158, v184, v185
	v_cvt_pk_bf16_f32 v159, v182, v183
	v_cvt_pk_bf16_f32 v160, v188, v189
	v_cvt_pk_bf16_f32 v161, v186, v187
	global_store_dwordx4 v[162:163], v[154:157], off
	global_store_dwordx4 v[164:165], v[158:161], off
	s_cbranch_execz .LBB0_1588
	s_branch .LBB0_1596

.LBB0_1596:
	s_nop 1
	v_or_b32_e32 v152, 32, v150
	v_cmp_lt_i32_e32 vcc, s70, v152
	s_and_saveexec_b64 s[8:9], vcc
	s_xor_b64 s[8:9], exec, s[8:9]
	s_add_i32 s31, s3, 0xffffc000
	s_lshr_b32 s31, s31, 8
	v_and_b32_e32 v138, 0xef, v152
	v_or_b32_e32 v138, 0x1000, v138
	v_mov_b32_e32 v151, s31
	s_andn2_saveexec_b64 s[8:9], s[8:9]
	s_ashr_i32 s31, s3, 12
	v_and_b32_e32 v138, 0xfef, v152
	v_mov_b32_e32 v151, s31
	s_or_b64 exec, exec, s[8:9]
	v_ashrrev_i32_e32 v153, 31, v152
	s_and_b64 vcc, exec, s[6:7]
	v_lshlrev_b64 v[152:153], 4, v[152:153]
	s_cbranch_vccnz .LBB0_1602
	v_and_b32_e32 v246, 0xff0, v152
	v_lshl_add_u64 v[154:155], s[20:21], 0, v[152:153]
	v_add_u32_e32 v246, v247, v246
	ds_read_b128 v[154:157], v246
	s_lshl_b32 s8, s28, 8
	s_or_b32 s8, s8, s63
	s_ashr_i32 s8, s8, 6
	v_lshl_add_u32 v160, v151, 3, s8
	v_mad_i64_i32 v[158:159], s[8:9], v160, s72, v[138:139]
	v_or_b32_e32 v160, 2, v160
	v_mad_i64_i32 v[160:161], s[8:9], v160, s72, v[138:139]
	v_mad_u64_u32 v[162:163], s[8:9], v158, s55, v[140:141]
	v_mad_i32_i24 v163, v159, s55, v163
	s_waitcnt lgkmcnt(0)
	v_mov_b32_e32 v164, v155
	v_mov_b32_e32 v165, v156
	v_mov_b32_e32 v155, v157
	v_pk_add_f32 v[154:155], v[164:165], v[154:155]
	v_mad_u64_u32 v[164:165], s[8:9], v160, s55, v[140:141]
	v_add_f32_e32 v154, v154, v155
	v_fmamk_f32 v154, v154, 0x3c000000, v175
	v_mul_f32_e32 v155, 0x4f800000, v154
	v_cmp_gt_f32_e32 vcc, s71, v154
	v_mad_i32_i24 v165, v161, s55, v165
	s_nop 0
	v_cndmask_b32_e32 v154, v154, v155, vcc
	v_sqrt_f32_e32 v155, v154
	s_nop 0
	v_add_u32_e32 v156, -1, v155
	v_add_u32_e32 v157, 1, v155
	v_fma_f32 v158, -v156, v155, v154
	v_fma_f32 v159, -v157, v155, v154
	v_cmp_ge_f32_e64 s[8:9], 0, v158
	s_nop 1
	v_cndmask_b32_e64 v155, v155, v156, s[8:9]
	v_cmp_lt_f32_e64 s[8:9], 0, v159
	s_nop 1
	v_cndmask_b32_e64 v155, v155, v157, s[8:9]
	v_mul_f32_e32 v156, 0x37800000, v155
	v_cndmask_b32_e32 v155, v155, v156, vcc
	v_cmp_class_f32_e32 vcc, v154, v176
	s_nop 1
	v_cndmask_b32_e32 v154, v155, v154, vcc
	v_div_scale_f32 v155, s[8:9], v154, v154, 1.0
	v_rcp_f32_e32 v156, v155
	v_div_scale_f32 v157, vcc, 1.0, v154, 1.0
	v_fma_f32 v158, -v155, v156, 1.0
	v_fmac_f32_e32 v156, v158, v156
	v_mul_f32_e32 v158, v157, v156
	v_fma_f32 v159, -v155, v158, v157
	v_fmac_f32_e32 v158, v159, v156
	v_fma_f32 v155, -v155, v158, v157
	v_div_fmas_f32 v155, v155, v156, v158
	v_div_fixup_f32 v154, v155, v154, 1.0
	v_pk_mul_f32 v[156:157], v[112:113], v[154:155] op_sel_hi:[1,0]
	v_pk_mul_f32 v[158:159], v[110:111], v[154:155] op_sel_hi:[1,0]
	v_pk_mul_f32 v[160:161], v[108:109], v[154:155] op_sel_hi:[1,0]
	v_pk_mul_f32 v[180:181], v[106:107], v[154:155] op_sel_hi:[1,0]
	v_pk_mul_f32 v[182:183], v[48:49], v[154:155] op_sel_hi:[1,0]
	v_pk_mul_f32 v[184:185], v[46:47], v[154:155] op_sel_hi:[1,0]
	v_pk_mul_f32 v[186:187], v[44:45], v[154:155] op_sel_hi:[1,0]
	v_pk_mul_f32 v[188:189], v[42:43], v[154:155] op_sel_hi:[1,0]
	v_cvt_pk_bf16_f32 v154, v158, v159
	v_cvt_pk_bf16_f32 v155, v156, v157
	v_cvt_pk_bf16_f32 v156, v180, v181
	v_cvt_pk_bf16_f32 v157, v160, v161
	v_cvt_pk_bf16_f32 v158, v184, v185
	v_cvt_pk_bf16_f32 v159, v182, v183
	v_cvt_pk_bf16_f32 v160, v188, v189
	v_cvt_pk_bf16_f32 v161, v186, v187
	global_store_dwordx4 v[162:163], v[154:157], off
	global_store_dwordx4 v[164:165], v[158:161], off
	s_cbranch_execz .LBB0_1603
	s_branch .LBB0_1611

.LBB0_1611:
	v_or_b32_e32 v150, 48, v150
	v_cmp_lt_i32_e32 vcc, s70, v150
	s_and_saveexec_b64 s[8:9], vcc
	s_xor_b64 s[8:9], exec, s[8:9]
	s_add_i32 s31, s3, 0xffffc000
	s_lshr_b32 s31, s31, 8
	v_or_b32_sdwa v138, v150, s67 dst_sel:DWORD dst_unused:UNUSED_PAD src0_sel:BYTE_0 src1_sel:DWORD
	v_mov_b32_e32 v152, s31
	s_andn2_saveexec_b64 s[8:9], s[8:9]
	s_ashr_i32 s31, s3, 12
	v_and_b32_e32 v138, 0xfff, v150
	v_mov_b32_e32 v152, s31
	s_or_b64 exec, exec, s[8:9]
	v_ashrrev_i32_e32 v151, 31, v150
	s_and_b64 vcc, exec, s[6:7]
	v_lshlrev_b64 v[150:151], 4, v[150:151]
	s_cbranch_vccnz .LBB0_1617
	v_and_b32_e32 v246, 0xff0, v150
	v_lshl_add_u64 v[154:155], s[20:21], 0, v[150:151]
	v_add_u32_e32 v246, v247, v246
	ds_read_b128 v[154:157], v246
	s_lshl_b32 s8, s28, 8
	s_or_b32 s8, s8, s63
	s_ashr_i32 s8, s8, 6
	v_lshl_add_u32 v153, v152, 3, s8
	v_mad_i64_i32 v[158:159], s[8:9], v153, s72, v[138:139]
	v_or_b32_e32 v153, 2, v153
	v_mad_i64_i32 v[160:161], s[8:9], v153, s72, v[138:139]
	v_mad_u64_u32 v[162:163], s[8:9], v158, s55, v[140:141]
	v_mad_i32_i24 v163, v159, s55, v163
	s_waitcnt lgkmcnt(0)
	v_mov_b32_e32 v164, v155
	v_mov_b32_e32 v165, v156
	v_mov_b32_e32 v155, v157
	v_pk_add_f32 v[154:155], v[164:165], v[154:155]
	v_mad_u64_u32 v[164:165], s[8:9], v160, s55, v[140:141]
	v_add_f32_e32 v153, v154, v155
	v_fmamk_f32 v153, v153, 0x3c000000, v175
	v_mul_f32_e32 v154, 0x4f800000, v153
	v_cmp_gt_f32_e32 vcc, s71, v153
	v_mad_i32_i24 v165, v161, s55, v165
	s_nop 0
	v_cndmask_b32_e32 v153, v153, v154, vcc
	v_sqrt_f32_e32 v154, v153
	s_nop 0
	v_add_u32_e32 v155, -1, v154
	v_add_u32_e32 v156, 1, v154
	v_fma_f32 v157, -v155, v154, v153
	v_fma_f32 v158, -v156, v154, v153
	v_cmp_ge_f32_e64 s[8:9], 0, v157
	s_nop 1
	v_cndmask_b32_e64 v154, v154, v155, s[8:9]
	v_cmp_lt_f32_e64 s[8:9], 0, v158
	s_nop 1
	v_cndmask_b32_e64 v154, v154, v156, s[8:9]
	v_mul_f32_e32 v155, 0x37800000, v154
	v_cndmask_b32_e32 v154, v154, v155, vcc
	v_cmp_class_f32_e32 vcc, v153, v176
	s_nop 1
	v_cndmask_b32_e32 v153, v154, v153, vcc
	v_div_scale_f32 v154, s[8:9], v153, v153, 1.0
	v_rcp_f32_e32 v155, v154
	v_div_scale_f32 v156, vcc, 1.0, v153, 1.0
	v_fma_f32 v157, -v154, v155, 1.0
	v_fmac_f32_e32 v155, v157, v155
	v_mul_f32_e32 v157, v156, v155
	v_fma_f32 v158, -v154, v157, v156
	v_fmac_f32_e32 v157, v158, v155
	v_fma_f32 v154, -v154, v157, v156
	v_div_fmas_f32 v154, v154, v155, v157
	v_div_fixup_f32 v154, v154, v153, 1.0
	v_pk_mul_f32 v[156:157], v[104:105], v[154:155] op_sel_hi:[1,0]
	v_pk_mul_f32 v[158:159], v[102:103], v[154:155] op_sel_hi:[1,0]
	v_pk_mul_f32 v[160:161], v[100:101], v[154:155] op_sel_hi:[1,0]
	v_pk_mul_f32 v[180:181], v[98:99], v[154:155] op_sel_hi:[1,0]
	v_pk_mul_f32 v[182:183], v[40:41], v[154:155] op_sel_hi:[1,0]
	v_pk_mul_f32 v[184:185], v[38:39], v[154:155] op_sel_hi:[1,0]
	v_pk_mul_f32 v[186:187], v[36:37], v[154:155] op_sel_hi:[1,0]
	v_pk_mul_f32 v[188:189], v[34:35], v[154:155] op_sel_hi:[1,0]
	v_cvt_pk_bf16_f32 v154, v158, v159
	v_cvt_pk_bf16_f32 v155, v156, v157
	v_cvt_pk_bf16_f32 v156, v180, v181
	v_cvt_pk_bf16_f32 v157, v160, v161
	v_cvt_pk_bf16_f32 v158, v184, v185
	v_cvt_pk_bf16_f32 v159, v182, v183
	v_cvt_pk_bf16_f32 v160, v188, v189
	v_cvt_pk_bf16_f32 v161, v186, v187
	global_store_dwordx4 v[162:163], v[154:157], off
	global_store_dwordx4 v[164:165], v[158:161], off
	s_cbranch_execz .LBB0_1618
	s_branch .LBB0_1626

.LBB0_1626:
	s_addk_i32 s3, 0x80
	s_nop 0
	v_or_b32_e32 v150, s3, v1
	v_cmp_lt_i32_e32 vcc, s70, v150
	s_and_saveexec_b64 s[8:9], vcc
	s_xor_b64 s[8:9], exec, s[8:9]
	s_add_i32 s31, s3, 0xffffc000
	s_lshr_b32 s31, s31, 8
	v_and_b32_e32 v138, 0xcf, v150
	v_or_b32_e32 v138, 0x1000, v138
	v_mov_b32_e32 v154, s31
	s_andn2_saveexec_b64 s[8:9], s[8:9]
	s_ashr_i32 s31, s3, 12
	v_and_b32_e32 v138, 0xfcf, v150
	v_mov_b32_e32 v154, s31
	s_or_b64 exec, exec, s[8:9]
	v_ashrrev_i32_e32 v151, 31, v150
	s_and_b64 vcc, exec, s[6:7]
	v_lshlrev_b64 v[152:153], 4, v[150:151]
	s_cbranch_vccnz .LBB0_1632
	v_and_b32_e32 v246, 0xff0, v152
	v_lshl_add_u64 v[156:157], s[20:21], 0, v[152:153]
	v_add_u32_e32 v246, v247, v246
	ds_read_b128 v[156:159], v246
	s_lshl_b32 s8, s28, 8
	s_or_b32 s8, s8, s63
	s_ashr_i32 s8, s8, 6
	v_lshl_add_u32 v151, v154, 3, s8
	v_mad_i64_i32 v[160:161], s[8:9], v151, s72, v[138:139]
	v_or_b32_e32 v151, 2, v151
	v_mad_i64_i32 v[162:163], s[8:9], v151, s72, v[138:139]
	v_mad_u64_u32 v[164:165], s[8:9], v160, s55, v[140:141]
	v_mad_i32_i24 v165, v161, s55, v165
	s_waitcnt lgkmcnt(0)
	v_mov_b32_e32 v180, v157
	v_mov_b32_e32 v181, v158
	v_mov_b32_e32 v157, v159
	v_pk_add_f32 v[156:157], v[180:181], v[156:157]
	v_mad_u64_u32 v[180:181], s[8:9], v162, s55, v[140:141]
	v_add_f32_e32 v151, v156, v157
	v_fmamk_f32 v151, v151, 0x3c000000, v175
	v_mul_f32_e32 v155, 0x4f800000, v151
	v_cmp_gt_f32_e32 vcc, s71, v151
	v_mad_i32_i24 v181, v163, s55, v181
	s_nop 0
	v_cndmask_b32_e32 v151, v151, v155, vcc
	v_sqrt_f32_e32 v155, v151
	s_nop 0
	v_add_u32_e32 v156, -1, v155
	v_add_u32_e32 v157, 1, v155
	v_fma_f32 v158, -v156, v155, v151
	v_fma_f32 v159, -v157, v155, v151
	v_cmp_ge_f32_e64 s[8:9], 0, v158
	s_nop 1
	v_cndmask_b32_e64 v155, v155, v156, s[8:9]
	v_cmp_lt_f32_e64 s[8:9], 0, v159
	s_nop 1
	v_cndmask_b32_e64 v155, v155, v157, s[8:9]
	v_mul_f32_e32 v156, 0x37800000, v155
	v_cndmask_b32_e32 v155, v155, v156, vcc
	v_cmp_class_f32_e32 vcc, v151, v176
	s_nop 1
	v_cndmask_b32_e32 v151, v155, v151, vcc
	v_div_scale_f32 v155, s[8:9], v151, v151, 1.0
	v_rcp_f32_e32 v156, v155
	v_div_scale_f32 v157, vcc, 1.0, v151, 1.0
	v_fma_f32 v158, -v155, v156, 1.0
	v_fmac_f32_e32 v156, v158, v156
	v_mul_f32_e32 v158, v157, v156
	v_fma_f32 v159, -v155, v158, v157
	v_fmac_f32_e32 v158, v159, v156
	v_fma_f32 v155, -v155, v158, v157
	v_div_fmas_f32 v155, v155, v156, v158
	v_div_fixup_f32 v156, v155, v151, 1.0
	v_pk_mul_f32 v[158:159], v[96:97], v[156:157] op_sel_hi:[1,0]
	v_pk_mul_f32 v[160:161], v[94:95], v[156:157] op_sel_hi:[1,0]
	v_pk_mul_f32 v[162:163], v[92:93], v[156:157] op_sel_hi:[1,0]
	v_pk_mul_f32 v[182:183], v[90:91], v[156:157] op_sel_hi:[1,0]
	v_pk_mul_f32 v[184:185], v[32:33], v[156:157] op_sel_hi:[1,0]
	v_pk_mul_f32 v[186:187], v[30:31], v[156:157] op_sel_hi:[1,0]
	v_pk_mul_f32 v[188:189], v[28:29], v[156:157] op_sel_hi:[1,0]
	v_pk_mul_f32 v[190:191], v[26:27], v[156:157] op_sel_hi:[1,0]
	v_cvt_pk_bf16_f32 v156, v160, v161
	v_cvt_pk_bf16_f32 v157, v158, v159
	v_cvt_pk_bf16_f32 v158, v182, v183
	v_cvt_pk_bf16_f32 v159, v162, v163
	v_cvt_pk_bf16_f32 v160, v186, v187
	v_cvt_pk_bf16_f32 v161, v184, v185
	v_cvt_pk_bf16_f32 v162, v190, v191
	v_cvt_pk_bf16_f32 v163, v188, v189
	global_store_dwordx4 v[164:165], v[156:159], off
	global_store_dwordx4 v[180:181], v[160:163], off
	s_cbranch_execz .LBB0_1633
	s_branch .LBB0_1641

.LBB0_1641:
	s_nop 1
	v_or_b32_e32 v152, 16, v150
	v_cmp_lt_i32_e32 vcc, s70, v152
	s_and_saveexec_b64 s[8:9], vcc
	s_xor_b64 s[8:9], exec, s[8:9]
	s_add_i32 s31, s3, 0xffffc000
	s_lshr_b32 s31, s31, 8
	v_and_b32_e32 v138, 0xdf, v152
	v_or_b32_e32 v138, 0x1000, v138
	v_mov_b32_e32 v151, s31
	s_andn2_saveexec_b64 s[8:9], s[8:9]
	s_ashr_i32 s31, s3, 12
	v_and_b32_e32 v138, 0xfdf, v152
	v_mov_b32_e32 v151, s31
	s_or_b64 exec, exec, s[8:9]
	v_ashrrev_i32_e32 v153, 31, v152
	s_and_b64 vcc, exec, s[6:7]
	v_lshlrev_b64 v[152:153], 4, v[152:153]
	s_cbranch_vccnz .LBB0_1647
	v_and_b32_e32 v246, 0xff0, v152
	v_lshl_add_u64 v[154:155], s[20:21], 0, v[152:153]
	v_add_u32_e32 v246, v247, v246
	ds_read_b128 v[154:157], v246
	s_lshl_b32 s8, s28, 8
	s_or_b32 s8, s8, s63
	s_ashr_i32 s8, s8, 6
	v_lshl_add_u32 v160, v151, 3, s8
	v_mad_i64_i32 v[158:159], s[8:9], v160, s72, v[138:139]
	v_or_b32_e32 v160, 2, v160
	v_mad_i64_i32 v[160:161], s[8:9], v160, s72, v[138:139]
	v_mad_u64_u32 v[162:163], s[8:9], v158, s55, v[140:141]
	v_mad_i32_i24 v163, v159, s55, v163
	s_waitcnt lgkmcnt(0)
	v_mov_b32_e32 v164, v155
	v_mov_b32_e32 v165, v156
	v_mov_b32_e32 v155, v157
	v_pk_add_f32 v[154:155], v[164:165], v[154:155]
	v_mad_u64_u32 v[164:165], s[8:9], v160, s55, v[140:141]
	v_add_f32_e32 v154, v154, v155
	v_fmamk_f32 v154, v154, 0x3c000000, v175
	v_mul_f32_e32 v155, 0x4f800000, v154
	v_cmp_gt_f32_e32 vcc, s71, v154
	v_mad_i32_i24 v165, v161, s55, v165
	s_nop 0
	v_cndmask_b32_e32 v154, v154, v155, vcc
	v_sqrt_f32_e32 v155, v154
	s_nop 0
	v_add_u32_e32 v156, -1, v155
	v_add_u32_e32 v157, 1, v155
	v_fma_f32 v158, -v156, v155, v154
	v_fma_f32 v159, -v157, v155, v154
	v_cmp_ge_f32_e64 s[8:9], 0, v158
	s_nop 1
	v_cndmask_b32_e64 v155, v155, v156, s[8:9]
	v_cmp_lt_f32_e64 s[8:9], 0, v159
	s_nop 1
	v_cndmask_b32_e64 v155, v155, v157, s[8:9]
	v_mul_f32_e32 v156, 0x37800000, v155
	v_cndmask_b32_e32 v155, v155, v156, vcc
	v_cmp_class_f32_e32 vcc, v154, v176
	s_nop 1
	v_cndmask_b32_e32 v154, v155, v154, vcc
	v_div_scale_f32 v155, s[8:9], v154, v154, 1.0
	v_rcp_f32_e32 v156, v155
	v_div_scale_f32 v157, vcc, 1.0, v154, 1.0
	v_fma_f32 v158, -v155, v156, 1.0
	v_fmac_f32_e32 v156, v158, v156
	v_mul_f32_e32 v158, v157, v156
	v_fma_f32 v159, -v155, v158, v157
	v_fmac_f32_e32 v158, v159, v156
	v_fma_f32 v155, -v155, v158, v157
	v_div_fmas_f32 v155, v155, v156, v158
	v_div_fixup_f32 v154, v155, v154, 1.0
	v_pk_mul_f32 v[156:157], v[88:89], v[154:155] op_sel_hi:[1,0]
	v_pk_mul_f32 v[158:159], v[86:87], v[154:155] op_sel_hi:[1,0]
	v_pk_mul_f32 v[160:161], v[84:85], v[154:155] op_sel_hi:[1,0]
	v_pk_mul_f32 v[180:181], v[82:83], v[154:155] op_sel_hi:[1,0]
	v_pk_mul_f32 v[182:183], v[24:25], v[154:155] op_sel_hi:[1,0]
	v_pk_mul_f32 v[184:185], v[22:23], v[154:155] op_sel_hi:[1,0]
	v_pk_mul_f32 v[186:187], v[20:21], v[154:155] op_sel_hi:[1,0]
	v_pk_mul_f32 v[188:189], v[18:19], v[154:155] op_sel_hi:[1,0]
	v_cvt_pk_bf16_f32 v154, v158, v159
	v_cvt_pk_bf16_f32 v155, v156, v157
	v_cvt_pk_bf16_f32 v156, v180, v181
	v_cvt_pk_bf16_f32 v157, v160, v161
	v_cvt_pk_bf16_f32 v158, v184, v185
	v_cvt_pk_bf16_f32 v159, v182, v183
	v_cvt_pk_bf16_f32 v160, v188, v189
	v_cvt_pk_bf16_f32 v161, v186, v187
	global_store_dwordx4 v[162:163], v[154:157], off
	global_store_dwordx4 v[164:165], v[158:161], off
	s_cbranch_execz .LBB0_1648
	s_branch .LBB0_1656

.LBB0_1656:
	s_nop 1
	v_or_b32_e32 v152, 32, v150
	v_cmp_lt_i32_e32 vcc, s70, v152
	s_and_saveexec_b64 s[8:9], vcc
	s_xor_b64 s[8:9], exec, s[8:9]
	s_add_i32 s31, s3, 0xffffc000
	s_lshr_b32 s31, s31, 8
	v_and_b32_e32 v138, 0xef, v152
	v_or_b32_e32 v138, 0x1000, v138
	v_mov_b32_e32 v151, s31
	s_andn2_saveexec_b64 s[8:9], s[8:9]
	s_ashr_i32 s31, s3, 12
	v_and_b32_e32 v138, 0xfef, v152
	v_mov_b32_e32 v151, s31
	s_or_b64 exec, exec, s[8:9]
	v_ashrrev_i32_e32 v153, 31, v152
	s_and_b64 vcc, exec, s[6:7]
	v_lshlrev_b64 v[152:153], 4, v[152:153]
	s_cbranch_vccnz .LBB0_1662
	v_and_b32_e32 v246, 0xff0, v152
	v_lshl_add_u64 v[154:155], s[20:21], 0, v[152:153]
	v_add_u32_e32 v246, v247, v246
	ds_read_b128 v[154:157], v246
	s_lshl_b32 s8, s28, 8
	s_or_b32 s8, s8, s63
	s_ashr_i32 s8, s8, 6
	v_lshl_add_u32 v160, v151, 3, s8
	v_mad_i64_i32 v[158:159], s[8:9], v160, s72, v[138:139]
	v_or_b32_e32 v160, 2, v160
	v_mad_i64_i32 v[160:161], s[8:9], v160, s72, v[138:139]
	v_mad_u64_u32 v[162:163], s[8:9], v158, s55, v[140:141]
	v_mad_i32_i24 v163, v159, s55, v163
	s_waitcnt lgkmcnt(0)
	v_mov_b32_e32 v164, v155
	v_mov_b32_e32 v165, v156
	v_mov_b32_e32 v155, v157
	v_pk_add_f32 v[154:155], v[164:165], v[154:155]
	v_mad_u64_u32 v[164:165], s[8:9], v160, s55, v[140:141]
	v_add_f32_e32 v154, v154, v155
	v_fmamk_f32 v154, v154, 0x3c000000, v175
	v_mul_f32_e32 v155, 0x4f800000, v154
	v_cmp_gt_f32_e32 vcc, s71, v154
	v_mad_i32_i24 v165, v161, s55, v165
	s_nop 0
	v_cndmask_b32_e32 v154, v154, v155, vcc
	v_sqrt_f32_e32 v155, v154
	s_nop 0
	v_add_u32_e32 v156, -1, v155
	v_add_u32_e32 v157, 1, v155
	v_fma_f32 v158, -v156, v155, v154
	v_fma_f32 v159, -v157, v155, v154
	v_cmp_ge_f32_e64 s[8:9], 0, v158
	s_nop 1
	v_cndmask_b32_e64 v155, v155, v156, s[8:9]
	v_cmp_lt_f32_e64 s[8:9], 0, v159
	s_nop 1
	v_cndmask_b32_e64 v155, v155, v157, s[8:9]
	v_mul_f32_e32 v156, 0x37800000, v155
	v_cndmask_b32_e32 v155, v155, v156, vcc
	v_cmp_class_f32_e32 vcc, v154, v176
	s_nop 1
	v_cndmask_b32_e32 v154, v155, v154, vcc
	v_div_scale_f32 v155, s[8:9], v154, v154, 1.0
	v_rcp_f32_e32 v156, v155
	v_div_scale_f32 v157, vcc, 1.0, v154, 1.0
	v_fma_f32 v158, -v155, v156, 1.0
	v_fmac_f32_e32 v156, v158, v156
	v_mul_f32_e32 v158, v157, v156
	v_fma_f32 v159, -v155, v158, v157
	v_fmac_f32_e32 v158, v159, v156
	v_fma_f32 v155, -v155, v158, v157
	v_div_fmas_f32 v155, v155, v156, v158
	v_div_fixup_f32 v154, v155, v154, 1.0
	v_pk_mul_f32 v[156:157], v[80:81], v[154:155] op_sel_hi:[1,0]
	v_pk_mul_f32 v[158:159], v[78:79], v[154:155] op_sel_hi:[1,0]
	v_pk_mul_f32 v[160:161], v[76:77], v[154:155] op_sel_hi:[1,0]
	v_pk_mul_f32 v[180:181], v[74:75], v[154:155] op_sel_hi:[1,0]
	v_pk_mul_f32 v[182:183], v[16:17], v[154:155] op_sel_hi:[1,0]
	v_pk_mul_f32 v[184:185], v[14:15], v[154:155] op_sel_hi:[1,0]
	v_pk_mul_f32 v[186:187], v[12:13], v[154:155] op_sel_hi:[1,0]
	v_pk_mul_f32 v[188:189], v[10:11], v[154:155] op_sel_hi:[1,0]
	v_cvt_pk_bf16_f32 v154, v158, v159
	v_cvt_pk_bf16_f32 v155, v156, v157
	v_cvt_pk_bf16_f32 v156, v180, v181
	v_cvt_pk_bf16_f32 v157, v160, v161
	v_cvt_pk_bf16_f32 v158, v184, v185
	v_cvt_pk_bf16_f32 v159, v182, v183
	v_cvt_pk_bf16_f32 v160, v188, v189
	v_cvt_pk_bf16_f32 v161, v186, v187
	global_store_dwordx4 v[162:163], v[154:157], off
	global_store_dwordx4 v[164:165], v[158:161], off
	s_cbranch_execz .LBB0_1663
	s_branch .LBB0_1671

.LBB0_1671:
	v_or_b32_e32 v150, 48, v150
	v_cmp_lt_i32_e32 vcc, s70, v150
	s_and_saveexec_b64 s[8:9], vcc
	s_xor_b64 s[8:9], exec, s[8:9]
	s_add_i32 s31, s3, 0xffffc000
	s_lshr_b32 s31, s31, 8
	v_or_b32_sdwa v138, v150, s67 dst_sel:DWORD dst_unused:UNUSED_PAD src0_sel:BYTE_0 src1_sel:DWORD
	v_mov_b32_e32 v152, s31
	s_andn2_saveexec_b64 s[8:9], s[8:9]
	s_ashr_i32 s3, s3, 12
	v_and_b32_e32 v138, 0xfff, v150
	v_mov_b32_e32 v152, s3
	s_or_b64 exec, exec, s[8:9]
	v_ashrrev_i32_e32 v151, 31, v150
	s_and_b64 vcc, exec, s[6:7]
	v_lshlrev_b64 v[150:151], 4, v[150:151]
	s_cbranch_vccnz .LBB0_1677
	v_and_b32_e32 v246, 0xff0, v150
	v_lshl_add_u64 v[154:155], s[20:21], 0, v[150:151]
	v_add_u32_e32 v246, v247, v246
	ds_read_b128 v[154:157], v246
	s_lshl_b32 s3, s28, 8
	s_or_b32 s3, s3, s63
	s_ashr_i32 s3, s3, 6
	v_lshl_add_u32 v153, v152, 3, s3
	v_mad_i64_i32 v[158:159], s[6:7], v153, s72, v[138:139]
	v_or_b32_e32 v153, 2, v153
	v_mad_i64_i32 v[160:161], s[6:7], v153, s72, v[138:139]
	v_mad_u64_u32 v[162:163], s[6:7], v158, s55, v[140:141]
	v_mad_i32_i24 v163, v159, s55, v163
	s_waitcnt lgkmcnt(0)
	v_mov_b32_e32 v164, v155
	v_mov_b32_e32 v165, v156
	v_mov_b32_e32 v155, v157
	v_pk_add_f32 v[154:155], v[164:165], v[154:155]
	v_mad_u64_u32 v[164:165], s[6:7], v160, s55, v[140:141]
	v_add_f32_e32 v153, v154, v155
	v_fmamk_f32 v153, v153, 0x3c000000, v175
	v_mul_f32_e32 v154, 0x4f800000, v153
	v_cmp_gt_f32_e32 vcc, s71, v153
	v_mad_i32_i24 v165, v161, s55, v165
	s_nop 0
	v_cndmask_b32_e32 v153, v153, v154, vcc
	v_sqrt_f32_e32 v154, v153
	s_nop 0
	v_add_u32_e32 v155, -1, v154
	v_add_u32_e32 v156, 1, v154
	v_fma_f32 v157, -v155, v154, v153
	v_fma_f32 v158, -v156, v154, v153
	v_cmp_ge_f32_e64 s[6:7], 0, v157
	s_nop 1
	v_cndmask_b32_e64 v154, v154, v155, s[6:7]
	v_cmp_lt_f32_e64 s[6:7], 0, v158
	s_nop 1
	v_cndmask_b32_e64 v154, v154, v156, s[6:7]
	v_mul_f32_e32 v155, 0x37800000, v154
	v_cndmask_b32_e32 v154, v154, v155, vcc
	v_cmp_class_f32_e32 vcc, v153, v176
	s_nop 1
	v_cndmask_b32_e32 v153, v154, v153, vcc
	v_div_scale_f32 v154, s[6:7], v153, v153, 1.0
	v_rcp_f32_e32 v155, v154
	v_div_scale_f32 v156, vcc, 1.0, v153, 1.0
	v_fma_f32 v157, -v154, v155, 1.0
	v_fmac_f32_e32 v155, v157, v155
	v_mul_f32_e32 v157, v156, v155
	v_fma_f32 v158, -v154, v157, v156
	v_fmac_f32_e32 v157, v158, v155
	v_fma_f32 v154, -v154, v157, v156
	v_div_fmas_f32 v154, v154, v155, v157
	v_div_fixup_f32 v154, v154, v153, 1.0
	v_pk_mul_f32 v[156:157], v[72:73], v[154:155] op_sel_hi:[1,0]
	v_pk_mul_f32 v[158:159], v[70:71], v[154:155] op_sel_hi:[1,0]
	v_pk_mul_f32 v[160:161], v[68:69], v[154:155] op_sel_hi:[1,0]
	v_pk_mul_f32 v[180:181], v[66:67], v[154:155] op_sel_hi:[1,0]
	v_pk_mul_f32 v[182:183], v[8:9], v[154:155] op_sel_hi:[1,0]
	v_pk_mul_f32 v[184:185], v[6:7], v[154:155] op_sel_hi:[1,0]
	v_pk_mul_f32 v[186:187], v[4:5], v[154:155] op_sel_hi:[1,0]
	v_pk_mul_f32 v[188:189], v[2:3], v[154:155] op_sel_hi:[1,0]
	v_cvt_pk_bf16_f32 v154, v158, v159
	v_cvt_pk_bf16_f32 v155, v156, v157
	v_cvt_pk_bf16_f32 v156, v180, v181
	v_cvt_pk_bf16_f32 v157, v160, v161
	v_cvt_pk_bf16_f32 v158, v184, v185
	v_cvt_pk_bf16_f32 v159, v182, v183
	v_cvt_pk_bf16_f32 v160, v188, v189
	v_cvt_pk_bf16_f32 v161, v186, v187
	global_store_dwordx4 v[162:163], v[154:157], off
	global_store_dwordx4 v[164:165], v[158:161], off
	s_cbranch_execz .LBB0_1678
	s_branch .LBB0_1686
